# NSA compressed pass 2: hand-written path for fully valid tiles (both row sets), pk_mul by 1/l, interleaved importance quad-sums, PV0 woven into set-1 exps
# speedup vs baseline: 1.0043x; 1.0028x over previous
; #define LAS __attribute__((address_space(3)))
; __device__ __forceinline__ void nsa_wg_task(bf16_t* zb, const bf16_t* kcb, const bf16_t* vctb, const bf16_t* vst, const bf16_t* vwt, int g, int T0, float* accb, LAS unsigned char* lds, int wave, int lane, int tid) {
;     ...
;         } else if (i < 2 * nc) {
;             const int kb0 = (i - nc) * 64; const bool n0 = kb0 < nv[0], n1 = kb0 < nv[1];
;             if (n0 || n1) { nsa_loadk(kbuf, offk0, offk1, ka, kb);
; #pragma unroll
;                 for (int r = 0; r < 2; ++r) if (r == 0 ? n0 : n1) { nsa_scores(ka, kb, q0[r], q1[r], S);
; #pragma unroll
;                     for (int st = 0; st < 4; ++st)
; #pragma unroll
;                         for (int j = 0; j < 4; ++j) { const float e = __builtin_amdgcn_exp2f(S[st][j]) * il[r]; S[st][j] = (kb0 + st * 16 + 4 * fq + j < nvl[r]) ? e : 0.f; }
; #pragma unroll
;                     for (int st = 0; st < 4; ++st) { const int sb = (kb0 >> 2) + 4 * st + fq; const float hb = 0.5f * S[st][3];
;                         const float a = quadsum((S[st][0] + S[st][1]) + (S[st][2] + hb)), b = quadsum(hb);
;                         if (h == 0) { LAS float* wp = wA + (r * 4 + ti) * 128 + sb; (void)__hip_atomic_fetch_add(wp, a, __ATOMIC_RELAXED, __HIP_MEMORY_SCOPE_WORKGROUP); if (sb + 1 < 128) (void)__hip_atomic_fetch_add(wp + 1, b, __ATOMIC_RELAXED, __HIP_MEMORY_SCOPE_WORKGROUP); } }
;                     nsa_pack(S, pf[r]); }
.Lp2_fast:
	v_add_u32_e32 v124, s45, v195
	v_add_u32_e32 v125, s45, v196
	ds_read_b128 v[132:135], v124
	ds_read_b128 v[136:139], v124 offset:2048
	ds_read_b128 v[140:143], v124 offset:4096
	ds_read_b128 v[144:147], v124 offset:6144
	ds_read_b128 v[148:151], v125
	ds_read_b128 v[152:155], v125 offset:2048
	ds_read_b128 v[116:119], v125 offset:4096
	ds_read_b128 v[120:123], v125 offset:6144
	v_add_u32_e32 v126, s45, v197
	v_add_u32_e32 v127, s45, v198
	v_add_u32_e32 v128, s45, v199
	v_add_u32_e32 v129, s45, v206
	v_lshl_or_b32 v65, s2, 4, v192
	s_nop 0
	v_lshl_add_u32 v165, v65, 2, v209
	s_waitcnt lgkmcnt(0)
	v_mfma_f32_16x16x32_bf16 v[16:19], v[132:135], v[60:63], 0
	v_mfma_f32_16x16x32_bf16 v[20:23], v[136:139], v[60:63], 0
	v_mfma_f32_16x16x32_bf16 v[24:27], v[140:143], v[60:63], 0
	v_mfma_f32_16x16x32_bf16 v[28:31], v[144:147], v[60:63], 0
	v_mfma_f32_16x16x32_bf16 v[16:19], v[148:151], v[72:75], v[16:19]
	v_mfma_f32_16x16x32_bf16 v[20:23], v[152:155], v[72:75], v[20:23]
	v_mfma_f32_16x16x32_bf16 v[24:27], v[116:119], v[72:75], v[24:27]
	v_mfma_f32_16x16x32_bf16 v[28:31], v[120:123], v[72:75], v[28:31]
	v_mfma_f32_16x16x32_bf16 v[32:35], v[132:135], v[76:79], 0
	v_mfma_f32_16x16x32_bf16 v[36:39], v[136:139], v[76:79], 0
	v_mfma_f32_16x16x32_bf16 v[40:43], v[140:143], v[76:79], 0
	v_mfma_f32_16x16x32_bf16 v[44:47], v[144:147], v[76:79], 0
	v_mfma_f32_16x16x32_bf16 v[32:35], v[148:151], v[80:83], v[32:35]
	v_mfma_f32_16x16x32_bf16 v[36:39], v[152:155], v[80:83], v[36:39]
	v_mfma_f32_16x16x32_bf16 v[40:43], v[116:119], v[80:83], v[40:43]
	v_mfma_f32_16x16x32_bf16 v[44:47], v[120:123], v[80:83], v[44:47]
	s_nop 3
	ds_read_b64 v[132:133], v126 offset:8192
	ds_read_b64 v[134:135], v127 offset:8192
	ds_read_b64 v[148:149], v128 offset:8192
	ds_read_b64 v[150:151], v129 offset:8192
	ds_read_b64 v[136:137], v126 offset:10240
	ds_read_b64 v[138:139], v127 offset:10240
	ds_read_b64 v[152:153], v128 offset:10240
	ds_read_b64 v[154:155], v129 offset:10240
	ds_read_b64 v[140:141], v126 offset:12288
	ds_read_b64 v[142:143], v127 offset:12288
	ds_read_b64 v[116:117], v128 offset:12288
	ds_read_b64 v[118:119], v129 offset:12288
	ds_read_b64 v[144:145], v126 offset:14336
	ds_read_b64 v[146:147], v127 offset:14336
	ds_read_b64 v[120:121], v128 offset:14336
	ds_read_b64 v[122:123], v129 offset:14336
	v_exp_f32_e32 v16, v16
	v_exp_f32_e32 v17, v17
	v_exp_f32_e32 v18, v18
	v_exp_f32_e32 v19, v19
	v_exp_f32_e32 v20, v20
	v_exp_f32_e32 v21, v21
	v_exp_f32_e32 v22, v22
	v_exp_f32_e32 v23, v23
	v_exp_f32_e32 v24, v24
	v_exp_f32_e32 v25, v25
	v_exp_f32_e32 v26, v26
	v_exp_f32_e32 v27, v27
	v_exp_f32_e32 v28, v28
	v_exp_f32_e32 v29, v29
	v_exp_f32_e32 v30, v30
	v_exp_f32_e32 v31, v31
	v_pk_mul_f32 v[16:17], v[16:17], v[248:249] op_sel:[0,1] op_sel_hi:[1,1]
	v_pk_mul_f32 v[18:19], v[18:19], v[248:249] op_sel:[0,1] op_sel_hi:[1,1]
	v_pk_mul_f32 v[20:21], v[20:21], v[248:249] op_sel:[0,1] op_sel_hi:[1,1]
	v_pk_mul_f32 v[22:23], v[22:23], v[248:249] op_sel:[0,1] op_sel_hi:[1,1]
	v_pk_mul_f32 v[24:25], v[24:25], v[248:249] op_sel:[0,1] op_sel_hi:[1,1]
	v_pk_mul_f32 v[26:27], v[26:27], v[248:249] op_sel:[0,1] op_sel_hi:[1,1]
	v_pk_mul_f32 v[28:29], v[28:29], v[248:249] op_sel:[0,1] op_sel_hi:[1,1]
	v_pk_mul_f32 v[30:31], v[30:31], v[248:249] op_sel:[0,1] op_sel_hi:[1,1]
	v_fma_f32 v242, 0.5, v19, v18
	v_fma_f32 v243, 0.5, v23, v22
	v_fma_f32 v252, 0.5, v27, v26
	v_fma_f32 v253, 0.5, v31, v30
	v_add_f32_e32 v48, v16, v17
	v_add_f32_e32 v49, v20, v21
	v_add_f32_e32 v50, v24, v25
	v_add_f32_e32 v51, v28, v29
	v_mul_f32_e32 v52, 0.5, v19
	v_mul_f32_e32 v53, 0.5, v23
	v_mul_f32_e32 v54, 0.5, v27
	v_mul_f32_e32 v55, 0.5, v31
	v_add_f32_e32 v48, v48, v242
	v_add_f32_e32 v49, v49, v243
	v_add_f32_e32 v50, v50, v252
	v_add_f32_e32 v51, v51, v253
	v_add_f32_dpp v52, v52, v52 quad_perm:[1,0,3,2] row_mask:0xf bank_mask:0xf bound_ctrl:1
	v_add_f32_dpp v53, v53, v53 quad_perm:[1,0,3,2] row_mask:0xf bank_mask:0xf bound_ctrl:1
	v_add_f32_dpp v54, v54, v54 quad_perm:[1,0,3,2] row_mask:0xf bank_mask:0xf bound_ctrl:1
	v_add_f32_dpp v55, v55, v55 quad_perm:[1,0,3,2] row_mask:0xf bank_mask:0xf bound_ctrl:1
	v_add_f32_dpp v48, v48, v48 quad_perm:[1,0,3,2] row_mask:0xf bank_mask:0xf bound_ctrl:1
	v_add_f32_dpp v49, v49, v49 quad_perm:[1,0,3,2] row_mask:0xf bank_mask:0xf bound_ctrl:1
	v_add_f32_dpp v50, v50, v50 quad_perm:[1,0,3,2] row_mask:0xf bank_mask:0xf bound_ctrl:1
	v_add_f32_dpp v51, v51, v51 quad_perm:[1,0,3,2] row_mask:0xf bank_mask:0xf bound_ctrl:1
	v_add_f32_dpp v52, v52, v52 quad_perm:[2,3,0,1] row_mask:0xf bank_mask:0xf bound_ctrl:1
	v_add_f32_dpp v53, v53, v53 quad_perm:[2,3,0,1] row_mask:0xf bank_mask:0xf bound_ctrl:1
	v_add_f32_dpp v54, v54, v54 quad_perm:[2,3,0,1] row_mask:0xf bank_mask:0xf bound_ctrl:1
	v_add_f32_dpp v55, v55, v55 quad_perm:[2,3,0,1] row_mask:0xf bank_mask:0xf bound_ctrl:1
	v_add_f32_dpp v48, v48, v48 quad_perm:[2,3,0,1] row_mask:0xf bank_mask:0xf bound_ctrl:1
	v_add_f32_dpp v49, v49, v49 quad_perm:[2,3,0,1] row_mask:0xf bank_mask:0xf bound_ctrl:1
	v_add_f32_dpp v50, v50, v50 quad_perm:[2,3,0,1] row_mask:0xf bank_mask:0xf bound_ctrl:1
	v_add_f32_dpp v51, v51, v51 quad_perm:[2,3,0,1] row_mask:0xf bank_mask:0xf bound_ctrl:1
	s_and_saveexec_b64 s[94:95], s[18:19]
	ds_add_f32 v165, v48 offset:0
	ds_add_f32 v165, v52 offset:4
	ds_add_f32 v165, v49 offset:16
	ds_add_f32 v165, v53 offset:20
	ds_add_f32 v165, v50 offset:32
	ds_add_f32 v165, v54 offset:36
	ds_add_f32 v165, v51 offset:48
	ds_add_f32 v165, v55 offset:52
	s_mov_b64 exec, s[94:95]
	v_cvt_pk_bf16_f32 v16, v16, v17
	v_cvt_pk_bf16_f32 v17, v18, v19
	v_cvt_pk_bf16_f32 v18, v20, v21
	v_cvt_pk_bf16_f32 v19, v22, v23
	v_cvt_pk_bf16_f32 v20, v24, v25
	v_cvt_pk_bf16_f32 v21, v26, v27
	v_cvt_pk_bf16_f32 v22, v28, v29
	v_cvt_pk_bf16_f32 v23, v30, v31
	s_waitcnt lgkmcnt(0)
; #define LAS __attribute__((address_space(3)))
; __device__ __forceinline__ void nsa_wg_task(bf16_t* zb, const bf16_t* kcb, const bf16_t* vctb, const bf16_t* vst, const bf16_t* vwt, int g, int T0, float* accb, LAS unsigned char* lds, int wave, int lane, int tid) {
;     ...
;                 for (int r = 0; r < 2; ++r) if (r == 0 ? n0 : n1) { nsa_scores(ka, kb, q0[r], q1[r], S);
; #pragma unroll
;                     for (int st = 0; st < 4; ++st)
; #pragma unroll
;                         for (int j = 0; j < 4; ++j) { const float e = __builtin_amdgcn_exp2f(S[st][j]) * il[r]; S[st][j] = (kb0 + st * 16 + 4 * fq + j < nvl[r]) ? e : 0.f; }
; #pragma unroll
;                     for (int st = 0; st < 4; ++st) { const int sb = (kb0 >> 2) + 4 * st + fq; const float hb = 0.5f * S[st][3];
;                         const float a = quadsum((S[st][0] + S[st][1]) + (S[st][2] + hb)), b = quadsum(hb);
;                         if (h == 0) { LAS float* wp = wA + (r * 4 + ti) * 128 + sb; (void)__hip_atomic_fetch_add(wp, a, __ATOMIC_RELAXED, __HIP_MEMORY_SCOPE_WORKGROUP); if (sb + 1 < 128) (void)__hip_atomic_fetch_add(wp + 1, b, __ATOMIC_RELAXED, __HIP_MEMORY_SCOPE_WORKGROUP); } }
;                     nsa_pack(S, pf[r]); }
;                 nsa_loadv(vbuf, offv00, offv01, offv10, offv11, vf);
; #pragma unroll
;                 for (int r = 0; r < 2; ++r) if (r == 0 ? n0 : n1) nsa_pv(vf, pf[r], O[r]); }
	s_nop 0
	v_exp_f32_e32 v32, v32
	v_exp_f32_e32 v33, v33
	v_mfma_f32_16x16x32_bf16 v[112:115], v[132:135], v[16:19], v[112:115]
	v_exp_f32_e32 v34, v34
	v_exp_f32_e32 v35, v35
	v_mfma_f32_16x16x32_bf16 v[108:111], v[136:139], v[16:19], v[108:111]
	v_exp_f32_e32 v36, v36
	v_exp_f32_e32 v37, v37
	v_mfma_f32_16x16x32_bf16 v[104:107], v[140:143], v[16:19], v[104:107]
	v_exp_f32_e32 v38, v38
	v_exp_f32_e32 v39, v39
	v_mfma_f32_16x16x32_bf16 v[100:103], v[144:147], v[16:19], v[100:103]
	v_exp_f32_e32 v40, v40
	v_exp_f32_e32 v41, v41
	v_mfma_f32_16x16x32_bf16 v[112:115], v[148:151], v[20:23], v[112:115]
	v_exp_f32_e32 v42, v42
	v_exp_f32_e32 v43, v43
	v_mfma_f32_16x16x32_bf16 v[108:111], v[152:155], v[20:23], v[108:111]
	v_exp_f32_e32 v44, v44
	v_exp_f32_e32 v45, v45
	v_mfma_f32_16x16x32_bf16 v[104:107], v[116:119], v[20:23], v[104:107]
	v_exp_f32_e32 v46, v46
	v_exp_f32_e32 v47, v47
	v_mfma_f32_16x16x32_bf16 v[100:103], v[120:123], v[20:23], v[100:103]
	v_pk_mul_f32 v[32:33], v[32:33], v[250:251] op_sel:[0,0] op_sel_hi:[1,0]
	v_pk_mul_f32 v[34:35], v[34:35], v[250:251] op_sel:[0,0] op_sel_hi:[1,0]
	v_pk_mul_f32 v[36:37], v[36:37], v[250:251] op_sel:[0,0] op_sel_hi:[1,0]
	v_pk_mul_f32 v[38:39], v[38:39], v[250:251] op_sel:[0,0] op_sel_hi:[1,0]
	v_pk_mul_f32 v[40:41], v[40:41], v[250:251] op_sel:[0,0] op_sel_hi:[1,0]
	v_pk_mul_f32 v[42:43], v[42:43], v[250:251] op_sel:[0,0] op_sel_hi:[1,0]
	v_pk_mul_f32 v[44:45], v[44:45], v[250:251] op_sel:[0,0] op_sel_hi:[1,0]
	v_pk_mul_f32 v[46:47], v[46:47], v[250:251] op_sel:[0,0] op_sel_hi:[1,0]
	v_fma_f32 v242, 0.5, v35, v34
	v_fma_f32 v243, 0.5, v39, v38
	v_fma_f32 v252, 0.5, v43, v42
	v_fma_f32 v253, 0.5, v47, v46
	v_add_f32_e32 v48, v32, v33
	v_add_f32_e32 v49, v36, v37
	v_add_f32_e32 v50, v40, v41
	v_add_f32_e32 v51, v44, v45
	v_mul_f32_e32 v52, 0.5, v35
	v_mul_f32_e32 v53, 0.5, v39
	v_mul_f32_e32 v54, 0.5, v43
	v_mul_f32_e32 v55, 0.5, v47
	v_add_f32_e32 v48, v48, v242
	v_add_f32_e32 v49, v49, v243
	v_add_f32_e32 v50, v50, v252
	v_add_f32_e32 v51, v51, v253
	v_add_f32_dpp v52, v52, v52 quad_perm:[1,0,3,2] row_mask:0xf bank_mask:0xf bound_ctrl:1
	v_add_f32_dpp v53, v53, v53 quad_perm:[1,0,3,2] row_mask:0xf bank_mask:0xf bound_ctrl:1
	v_add_f32_dpp v54, v54, v54 quad_perm:[1,0,3,2] row_mask:0xf bank_mask:0xf bound_ctrl:1
	v_add_f32_dpp v55, v55, v55 quad_perm:[1,0,3,2] row_mask:0xf bank_mask:0xf bound_ctrl:1
	v_add_f32_dpp v48, v48, v48 quad_perm:[1,0,3,2] row_mask:0xf bank_mask:0xf bound_ctrl:1
	v_add_f32_dpp v49, v49, v49 quad_perm:[1,0,3,2] row_mask:0xf bank_mask:0xf bound_ctrl:1
	v_add_f32_dpp v50, v50, v50 quad_perm:[1,0,3,2] row_mask:0xf bank_mask:0xf bound_ctrl:1
	v_add_f32_dpp v51, v51, v51 quad_perm:[1,0,3,2] row_mask:0xf bank_mask:0xf bound_ctrl:1
	v_add_f32_dpp v52, v52, v52 quad_perm:[2,3,0,1] row_mask:0xf bank_mask:0xf bound_ctrl:1
	v_add_f32_dpp v53, v53, v53 quad_perm:[2,3,0,1] row_mask:0xf bank_mask:0xf bound_ctrl:1
	v_add_f32_dpp v54, v54, v54 quad_perm:[2,3,0,1] row_mask:0xf bank_mask:0xf bound_ctrl:1
	v_add_f32_dpp v55, v55, v55 quad_perm:[2,3,0,1] row_mask:0xf bank_mask:0xf bound_ctrl:1
	v_add_f32_dpp v48, v48, v48 quad_perm:[2,3,0,1] row_mask:0xf bank_mask:0xf bound_ctrl:1
	v_add_f32_dpp v49, v49, v49 quad_perm:[2,3,0,1] row_mask:0xf bank_mask:0xf bound_ctrl:1
	v_add_f32_dpp v50, v50, v50 quad_perm:[2,3,0,1] row_mask:0xf bank_mask:0xf bound_ctrl:1
	v_add_f32_dpp v51, v51, v51 quad_perm:[2,3,0,1] row_mask:0xf bank_mask:0xf bound_ctrl:1
	s_and_saveexec_b64 s[94:95], s[18:19]
	ds_add_f32 v165, v48 offset:2048
	ds_add_f32 v165, v52 offset:2052
	ds_add_f32 v165, v49 offset:2064
	ds_add_f32 v165, v53 offset:2068
	ds_add_f32 v165, v50 offset:2080
	ds_add_f32 v165, v54 offset:2084
	ds_add_f32 v165, v51 offset:2096
	ds_add_f32 v165, v55 offset:2100
	s_mov_b64 exec, s[94:95]
	v_cvt_pk_bf16_f32 v32, v32, v33
	v_cvt_pk_bf16_f32 v33, v34, v35
	v_cvt_pk_bf16_f32 v34, v36, v37
	v_cvt_pk_bf16_f32 v35, v38, v39
	v_cvt_pk_bf16_f32 v36, v40, v41
	v_cvt_pk_bf16_f32 v37, v42, v43
	v_cvt_pk_bf16_f32 v38, v44, v45
	v_cvt_pk_bf16_f32 v39, v46, v47
	s_nop 1
	v_mfma_f32_16x16x32_bf16 v[96:99], v[132:135], v[32:35], v[96:99]
	v_mfma_f32_16x16x32_bf16 v[92:95], v[136:139], v[32:35], v[92:95]
	v_mfma_f32_16x16x32_bf16 v[88:91], v[140:143], v[32:35], v[88:91]
	v_mfma_f32_16x16x32_bf16 v[84:87], v[144:147], v[32:35], v[84:87]
	v_mfma_f32_16x16x32_bf16 v[96:99], v[148:151], v[36:39], v[96:99]
	v_mfma_f32_16x16x32_bf16 v[92:95], v[152:155], v[36:39], v[92:95]
	v_mfma_f32_16x16x32_bf16 v[88:91], v[116:119], v[36:39], v[88:91]
	v_mfma_f32_16x16x32_bf16 v[84:87], v[120:123], v[36:39], v[84:87]
	s_nop 7
	s_branch .LBB0_345

; __device__ __forceinline__ void nsa_wg_task(bf16_t* zb, const bf16_t* kcb, const bf16_t* vctb, const bf16_t* vst, const bf16_t* vwt, int g, int T0, float* accb, LAS unsigned char* lds, int wave, int lane, int tid) {
;     ...
;         } else if (i < 2 * nc) {
;             const int kb0 = (i - nc) * 64; const bool n0 = kb0 < nv[0], n1 = kb0 < nv[1];
;             if (n0 || n1) { nsa_loadk(kbuf, offk0, offk1, ka, kb);
.LBB0_260:
	s_andn2_b64 vcc, exec, s[20:21]
	s_cbranch_vccnz .LBB0_343
	s_sub_i32 s2, s44, s70
	s_lshl_b32 s20, s2, 6
	s_cmp_lt_i32 s20, s0
	s_cselect_b64 s[22:23], -1, 0
	s_cmp_lt_i32 s20, s86
	s_cselect_b64 s[24:25], -1, 0
	s_or_b64 s[28:29], s[22:23], s[24:25]
	s_cmp_eq_u32 s44, s73
	s_cbranch_scc1 .Lp2_slow
	s_add_i32 s94, s20, 64
	s_sub_i32 s95, s88, 31
	s_ashr_i32 s95, s95, 4
	s_add_i32 s95, s95, 1
	s_cmp_le_i32 s94, s95
	s_cbranch_scc0 .Lp2_slow
	s_sub_i32 s95, s89, 31
	s_ashr_i32 s95, s95, 4
	s_add_i32 s95, s95, 1
	s_cmp_le_i32 s94, s95
	s_cbranch_scc1 .Lp2_fast
.Lp2_slow:
	s_waitcnt lgkmcnt(0)
	v_mov_b64_e32 v[30:31], v[14:15]
	v_mov_b64_e32 v[32:33], v[84:85]
	v_mov_b64_e32 v[36:37], v[88:89]
	v_mov_b64_e32 v[40:41], v[92:93]
	v_mov_b64_e32 v[44:45], v[96:97]
	v_mov_b64_e32 v[48:49], v[100:101]
	v_mov_b64_e32 v[52:53], v[104:105]
	v_mov_b64_e32 v[118:119], v[110:111]
	v_mov_b64_e32 v[122:123], v[114:115]
	s_andn2_b64 vcc, exec, s[28:29]
	v_mov_b64_e32 v[28:29], v[12:13]
	v_mov_b64_e32 v[26:27], v[10:11]
	v_mov_b64_e32 v[24:25], v[8:9]
	v_mov_b64_e32 v[22:23], v[6:7]
	v_mov_b64_e32 v[20:21], v[4:5]
	v_mov_b64_e32 v[18:19], v[2:3]
	v_mov_b64_e32 v[16:17], v[0:1]
	v_mov_b64_e32 v[34:35], v[86:87]
	v_mov_b64_e32 v[38:39], v[90:91]
	v_mov_b64_e32 v[42:43], v[94:95]
	v_mov_b64_e32 v[46:47], v[98:99]
	v_mov_b64_e32 v[50:51], v[102:103]
	v_mov_b64_e32 v[54:55], v[106:107]
	v_mov_b64_e32 v[116:117], v[108:109]
	v_mov_b64_e32 v[120:121], v[112:113]
	s_cbranch_vccnz .LBB0_294
	v_add_u32_e32 v16, s45, v195
	v_add_u32_e32 v17, s45, v196
	ds_read_b128 v[116:119], v16
	ds_read_b128 v[52:55], v16 offset:2048
	ds_read_b128 v[120:123], v17
	ds_read_b128 v[36:39], v17 offset:2048
	ds_read_b128 v[48:51], v16 offset:4096
	ds_read_b128 v[44:47], v16 offset:6144
	ds_read_b128 v[40:43], v17 offset:4096
	ds_read_b128 v[32:35], v17 offset:6144
	v_cndmask_b32_e64 v16, 0, 1, s[22:23]
	v_add_u32_e32 v124, s20, v166
	v_cmp_ne_u32_e64 s[20:21], 1, v16
	v_mov_b64_e32 v[30:31], v[14:15]
	v_lshl_or_b32 v65, s2, 4, v192
	s_andn2_b64 vcc, exec, s[22:23]
	v_or_b32_e32 v127, 1, v124
	v_or_b32_e32 v126, 2, v124
	v_or_b32_e32 v125, 3, v124
	v_mov_b64_e32 v[28:29], v[12:13]
	v_mov_b64_e32 v[26:27], v[10:11]
	v_mov_b64_e32 v[24:25], v[8:9]
	v_mov_b64_e32 v[22:23], v[6:7]
	v_mov_b64_e32 v[20:21], v[4:5]
	v_mov_b64_e32 v[18:19], v[2:3]
	v_mov_b64_e32 v[16:17], v[0:1]
	s_cbranch_vccnz .LBB0_276
	s_waitcnt lgkmcnt(0)
	v_mfma_f32_16x16x32_bf16 v[16:19], v[116:119], v[60:63], 0
	v_cmp_lt_i32_e32 vcc, v124, v161
	v_mfma_f32_16x16x32_bf16 v[16:19], v[120:123], v[72:75], v[16:19]
	v_mfma_f32_16x16x32_bf16 v[20:23], v[52:55], v[60:63], 0
	v_mfma_f32_16x16x32_bf16 v[132:135], v[44:47], v[60:63], 0
	s_nop 5
	v_exp_f32_e32 v16, v16
	v_exp_f32_e32 v17, v17
	v_exp_f32_e32 v18, v18
	v_exp_f32_e32 v24, v19
	v_mul_f32_e32 v16, v249, v16
	v_mul_f32_e32 v17, v249, v17
	v_cndmask_b32_e32 v28, 0, v16, vcc
	v_cmp_lt_i32_e32 vcc, v127, v161
	v_mul_f32_e32 v25, v249, v18
	v_mul_f32_e32 v24, v249, v24
	v_cndmask_b32_e32 v29, 0, v17, vcc
	v_mfma_f32_16x16x32_bf16 v[16:19], v[48:51], v[60:63], 0
	v_cmp_lt_i32_e32 vcc, v126, v161
	s_nop 1
	v_cndmask_b32_e32 v128, 0, v25, vcc
	v_cmp_lt_i32_e32 vcc, v125, v161
	s_nop 1
	v_cndmask_b32_e32 v129, 0, v24, vcc
	v_mfma_f32_16x16x32_bf16 v[24:27], v[36:39], v[72:75], v[20:23]
	v_mul_f32_e32 v30, 0.5, v129
	s_nop 1
	v_add_f32_e32 v20, v28, v29
	v_fma_f32 v21, 0.5, v129, v128
	v_add_f32_e32 v31, v20, v21
	v_mfma_f32_16x16x32_bf16 v[20:23], v[40:43], v[72:75], v[16:19]
	v_mov_b32_dpp v30, v30 quad_perm:[1,0,3,2] row_mask:0xf bank_mask:0xf bound_ctrl:1
	v_add_f32_dpp v130, v31, v31 quad_perm:[1,0,3,2] row_mask:0xf bank_mask:0xf bound_ctrl:1
	v_fmac_f32_e32 v30, 0.5, v129
	v_mfma_f32_16x16x32_bf16 v[16:19], v[32:35], v[72:75], v[132:135]
	v_mov_b32_dpp v131, v130 quad_perm:[2,3,0,1] row_mask:0xf bank_mask:0xf bound_ctrl:1
	v_mov_b32_dpp v31, v30 quad_perm:[2,3,0,1] row_mask:0xf bank_mask:0xf bound_ctrl:1
	s_and_saveexec_b64 s[22:23], s[18:19]
	s_cbranch_execz .LBB0_266
	v_add_f32_e32 v131, v130, v131
	v_lshl_add_u32 v130, v65, 2, v209
	s_waitcnt vmcnt(0)
	ds_add_f32 v130, v131
	s_movk_i32 s2, 0x7f
	v_cmp_gt_i32_e32 vcc, s2, v65
	s_and_b64 exec, exec, vcc
	v_add_f32_e32 v30, v30, v31
	ds_add_f32 v130, v30 offset:4
